# P2 chunk product: vT fragment fetch ring three blocks deep (extra block in v[236:251]), waits 11..8
# baseline (speedup 1.0000x reference)
.LBB0_268:
	s_lshl_b32 s46, s46, 3
	s_ashr_i32 s47, s46, 31
	s_lshl_b64 s[46:47], s[46:47], 11
	s_lshl_b32 s0, s45, 9
	s_add_u32 s0, s0, s59
	s_addc_u32 s45, 0, s60
	v_mov_b32_e32 v234, v62
	s_add_u32 s0, s0, s46
	s_addc_u32 s45, s45, s47
	v_and_b32_e32 v235, 15, v234
	v_or_b32_e32 v2, s0, v235
	v_mov_b32_e32 v3, s45
	v_bfe_u32 v214, v234, 4, 2
	v_lshlrev_b64 v[2:3], 6, v[2:3]
	v_lshrrev_b32_e32 v12, 4, v234
	v_lshl_add_u64 v[2:3], s[12:13], 0, v[2:3]
	v_lshlrev_b32_e32 v64, 4, v214
	v_bitop3_b32 v12, v12, v235, 3 bitop3:0x6c
	v_lshl_add_u64 v[2:3], v[2:3], 0, v[64:65]
	v_lshlrev_b32_e32 v64, 9, v235
	v_lshlrev_b32_e32 v12, 4, v12
	v_add3_u32 v60, 0, v12, v64
	global_load_dwordx4 v[4:7], v[2:3], off
	global_load_dwordx4 v[8:11], v[2:3], off offset:1024
	ds_read_b128 v[12:15], v60
	ds_read_b128 v[16:19], v60 offset:8192
	global_load_dwordx4 v[24:27], v[2:3], off offset:2048
	global_load_dwordx4 v[32:35], v[2:3], off offset:3072
	ds_read_b128 v[52:55], v60 offset:16384
	ds_read_b128 v[56:59], v60 offset:24576
	ds_read_b128 v[126:129], v60 offset:32768
	ds_read_b128 v[130:133], v60 offset:40960
	ds_read_b128 v[158:161], v60 offset:49152
	ds_read_b128 v[162:165], v60 offset:57344
	v_add_co_u32_e32 v60, vcc, s69, v2
	s_nop 1
	v_addc_co_u32_e32 v61, vcc, 0, v3, vcc
	global_load_dwordx4 v[178:181], v[60:61], off
	global_load_dwordx4 v[182:185], v[60:61], off offset:1024
	global_load_dwordx4 v[186:189], v[60:61], off offset:2048
	global_load_dwordx4 v[190:193], v[60:61], off offset:3072
	v_add_co_u32_e32 v60, vcc, s70, v2
	s_nop 1
	v_addc_co_u32_e32 v61, vcc, 0, v3, vcc
	global_load_dwordx4 v[236:239], v[60:61], off
	global_load_dwordx4 v[240:243], v[60:61], off offset:1024
	global_load_dwordx4 v[244:247], v[60:61], off offset:2048
	global_load_dwordx4 v[248:251], v[60:61], off offset:3072
	s_waitcnt vmcnt(11) lgkmcnt(7)
	v_mfma_f32_16x16x32_bf16 v[20:23], v[12:15], v[4:7], 0
	s_waitcnt vmcnt(10)
	v_mfma_f32_16x16x32_bf16 v[28:31], v[12:15], v[8:11], 0
	s_waitcnt vmcnt(9)
	v_mfma_f32_16x16x32_bf16 v[36:39], v[12:15], v[24:27], 0
	s_waitcnt vmcnt(8)
	v_mfma_f32_16x16x32_bf16 v[12:15], v[12:15], v[32:35], 0
	s_waitcnt lgkmcnt(6)
	v_mfma_f32_16x16x32_bf16 v[40:43], v[16:19], v[4:7], 0
	v_mfma_f32_16x16x32_bf16 v[44:47], v[16:19], v[8:11], 0
	v_mfma_f32_16x16x32_bf16 v[48:51], v[16:19], v[24:27], 0
	v_mfma_f32_16x16x32_bf16 v[16:19], v[16:19], v[32:35], 0
	s_waitcnt lgkmcnt(5)
	v_mfma_f32_16x16x32_bf16 v[72:75], v[52:55], v[4:7], 0
	v_mfma_f32_16x16x32_bf16 v[76:79], v[52:55], v[8:11], 0
	v_mfma_f32_16x16x32_bf16 v[80:83], v[52:55], v[24:27], 0
	v_mfma_f32_16x16x32_bf16 v[52:55], v[52:55], v[32:35], 0
	s_waitcnt lgkmcnt(4)
	v_mfma_f32_16x16x32_bf16 v[114:117], v[56:59], v[4:7], 0
	v_mfma_f32_16x16x32_bf16 v[118:121], v[56:59], v[8:11], 0
	v_mfma_f32_16x16x32_bf16 v[122:125], v[56:59], v[24:27], 0
	v_mfma_f32_16x16x32_bf16 v[56:59], v[56:59], v[32:35], 0
	s_waitcnt lgkmcnt(3)
	v_mfma_f32_16x16x32_bf16 v[134:137], v[126:129], v[4:7], 0
	v_mfma_f32_16x16x32_bf16 v[138:141], v[126:129], v[8:11], 0
	v_mfma_f32_16x16x32_bf16 v[142:145], v[126:129], v[24:27], 0
	v_mfma_f32_16x16x32_bf16 v[126:129], v[126:129], v[32:35], 0
	s_waitcnt lgkmcnt(2)
	v_mfma_f32_16x16x32_bf16 v[146:149], v[130:133], v[4:7], 0
	v_mfma_f32_16x16x32_bf16 v[150:153], v[130:133], v[8:11], 0
	v_mfma_f32_16x16x32_bf16 v[154:157], v[130:133], v[24:27], 0
	v_mfma_f32_16x16x32_bf16 v[130:133], v[130:133], v[32:35], 0
	s_waitcnt lgkmcnt(1)
	v_mfma_f32_16x16x32_bf16 v[166:169], v[158:161], v[4:7], 0
	v_mfma_f32_16x16x32_bf16 v[170:173], v[158:161], v[8:11], 0
	v_mfma_f32_16x16x32_bf16 v[174:177], v[158:161], v[24:27], 0
	v_mfma_f32_16x16x32_bf16 v[158:161], v[158:161], v[32:35], 0
	s_waitcnt lgkmcnt(0)
	v_mfma_f32_16x16x32_bf16 v[4:7], v[162:165], v[4:7], 0
	v_mfma_f32_16x16x32_bf16 v[8:11], v[162:165], v[8:11], 0
	v_mfma_f32_16x16x32_bf16 v[24:27], v[162:165], v[24:27], 0
	v_mfma_f32_16x16x32_bf16 v[32:35], v[162:165], v[32:35], 0
	v_add_co_u32_e32 v60, vcc, s67, v2
	s_nop 1
	v_addc_co_u32_e32 v61, vcc, 0, v3, vcc
	global_load_dwordx4 v[162:165], v[60:61], off
	global_load_dwordx4 v[194:197], v[60:61], off offset:1024
	global_load_dwordx4 v[198:201], v[60:61], off offset:2048
	global_load_dwordx4 v[202:205], v[60:61], off offset:3072
	v_bitop3_b32 v60, v214, v235, 4 bitop3:0x36
	v_lshlrev_b32_e32 v60, 4, v60
	v_add3_u32 v60, 0, v60, v64
	ds_read_b128 v[206:209], v60
	ds_read_b128 v[210:213], v60 offset:8192
	s_waitcnt vmcnt(11) lgkmcnt(1)
	v_mfma_f32_16x16x32_bf16 v[20:23], v[206:209], v[178:181], v[20:23]
	s_waitcnt vmcnt(10)
	v_mfma_f32_16x16x32_bf16 v[28:31], v[206:209], v[182:185], v[28:31]
	s_waitcnt vmcnt(9)
	v_mfma_f32_16x16x32_bf16 v[36:39], v[206:209], v[186:189], v[36:39]
	s_waitcnt vmcnt(8)
	v_mfma_f32_16x16x32_bf16 v[12:15], v[206:209], v[190:193], v[12:15]
	s_waitcnt lgkmcnt(0)
	v_mfma_f32_16x16x32_bf16 v[40:43], v[210:213], v[178:181], v[40:43]
	v_mfma_f32_16x16x32_bf16 v[44:47], v[210:213], v[182:185], v[44:47]
	v_mfma_f32_16x16x32_bf16 v[48:51], v[210:213], v[186:189], v[48:51]
	v_mfma_f32_16x16x32_bf16 v[16:19], v[210:213], v[190:193], v[16:19]
	ds_read_b128 v[206:209], v60 offset:16384
	ds_read_b128 v[210:213], v60 offset:24576
	s_waitcnt lgkmcnt(1)
	v_mfma_f32_16x16x32_bf16 v[72:75], v[206:209], v[178:181], v[72:75]
	v_mfma_f32_16x16x32_bf16 v[76:79], v[206:209], v[182:185], v[76:79]
	v_mfma_f32_16x16x32_bf16 v[80:83], v[206:209], v[186:189], v[80:83]
	v_mfma_f32_16x16x32_bf16 v[52:55], v[206:209], v[190:193], v[52:55]
	s_waitcnt lgkmcnt(0)
	v_mfma_f32_16x16x32_bf16 v[114:117], v[210:213], v[178:181], v[114:117]
	v_mfma_f32_16x16x32_bf16 v[118:121], v[210:213], v[182:185], v[118:121]
	v_mfma_f32_16x16x32_bf16 v[122:125], v[210:213], v[186:189], v[122:125]
	v_mfma_f32_16x16x32_bf16 v[56:59], v[210:213], v[190:193], v[56:59]
	ds_read_b128 v[206:209], v60 offset:32768
	ds_read_b128 v[210:213], v60 offset:40960
	s_waitcnt lgkmcnt(1)
	v_mfma_f32_16x16x32_bf16 v[134:137], v[206:209], v[178:181], v[134:137]
	v_mfma_f32_16x16x32_bf16 v[138:141], v[206:209], v[182:185], v[138:141]
	v_mfma_f32_16x16x32_bf16 v[142:145], v[206:209], v[186:189], v[142:145]
	v_mfma_f32_16x16x32_bf16 v[126:129], v[206:209], v[190:193], v[126:129]
	s_waitcnt lgkmcnt(0)
	v_mfma_f32_16x16x32_bf16 v[146:149], v[210:213], v[178:181], v[146:149]
	v_mfma_f32_16x16x32_bf16 v[150:153], v[210:213], v[182:185], v[150:153]
	v_mfma_f32_16x16x32_bf16 v[154:157], v[210:213], v[186:189], v[154:157]
	v_mfma_f32_16x16x32_bf16 v[130:133], v[210:213], v[190:193], v[130:133]
	ds_read_b128 v[206:209], v60 offset:49152
	ds_read_b128 v[210:213], v60 offset:57344
	s_waitcnt lgkmcnt(1)
	v_mfma_f32_16x16x32_bf16 v[166:169], v[206:209], v[178:181], v[166:169]
	v_mfma_f32_16x16x32_bf16 v[170:173], v[206:209], v[182:185], v[170:173]
	v_mfma_f32_16x16x32_bf16 v[174:177], v[206:209], v[186:189], v[174:177]
	v_mfma_f32_16x16x32_bf16 v[158:161], v[206:209], v[190:193], v[158:161]
	s_waitcnt lgkmcnt(0)
	v_mfma_f32_16x16x32_bf16 v[4:7], v[210:213], v[178:181], v[4:7]
	v_mfma_f32_16x16x32_bf16 v[8:11], v[210:213], v[182:185], v[8:11]
	v_mfma_f32_16x16x32_bf16 v[24:27], v[210:213], v[186:189], v[24:27]
	v_mfma_f32_16x16x32_bf16 v[32:35], v[210:213], v[190:193], v[32:35]
	v_add_co_u32_e32 v60, vcc, s71, v2
	s_nop 1
	v_addc_co_u32_e32 v61, vcc, 0, v3, vcc
	global_load_dwordx4 v[178:181], v[60:61], off
	global_load_dwordx4 v[182:185], v[60:61], off offset:1024
	global_load_dwordx4 v[186:189], v[60:61], off offset:2048
	global_load_dwordx4 v[190:193], v[60:61], off offset:3072
	v_bitop3_b32 v60, v214, v235, 8 bitop3:0x36
	v_lshlrev_b32_e32 v60, 4, v60
	v_add3_u32 v60, 0, v60, v64
	ds_read_b128 v[206:209], v60
	ds_read_b128 v[210:213], v60 offset:8192
	s_waitcnt vmcnt(11) lgkmcnt(1)
	v_mfma_f32_16x16x32_bf16 v[20:23], v[206:209], v[236:239], v[20:23]
	s_waitcnt vmcnt(10)
	v_mfma_f32_16x16x32_bf16 v[28:31], v[206:209], v[240:243], v[28:31]
	s_waitcnt vmcnt(9)
	v_mfma_f32_16x16x32_bf16 v[36:39], v[206:209], v[244:247], v[36:39]
	s_waitcnt vmcnt(8)
	v_mfma_f32_16x16x32_bf16 v[12:15], v[206:209], v[248:251], v[12:15]
	s_waitcnt lgkmcnt(0)
	v_mfma_f32_16x16x32_bf16 v[40:43], v[210:213], v[236:239], v[40:43]
	v_mfma_f32_16x16x32_bf16 v[44:47], v[210:213], v[240:243], v[44:47]
	v_mfma_f32_16x16x32_bf16 v[48:51], v[210:213], v[244:247], v[48:51]
	v_mfma_f32_16x16x32_bf16 v[16:19], v[210:213], v[248:251], v[16:19]
	ds_read_b128 v[206:209], v60 offset:16384
	ds_read_b128 v[210:213], v60 offset:24576
	s_waitcnt lgkmcnt(1)
	v_mfma_f32_16x16x32_bf16 v[72:75], v[206:209], v[236:239], v[72:75]
	v_mfma_f32_16x16x32_bf16 v[76:79], v[206:209], v[240:243], v[76:79]
	v_mfma_f32_16x16x32_bf16 v[80:83], v[206:209], v[244:247], v[80:83]
	v_mfma_f32_16x16x32_bf16 v[52:55], v[206:209], v[248:251], v[52:55]
	s_waitcnt lgkmcnt(0)
	v_mfma_f32_16x16x32_bf16 v[114:117], v[210:213], v[236:239], v[114:117]
	v_mfma_f32_16x16x32_bf16 v[118:121], v[210:213], v[240:243], v[118:121]
	v_mfma_f32_16x16x32_bf16 v[122:125], v[210:213], v[244:247], v[122:125]
	v_mfma_f32_16x16x32_bf16 v[56:59], v[210:213], v[248:251], v[56:59]
	ds_read_b128 v[206:209], v60 offset:32768
	ds_read_b128 v[210:213], v60 offset:40960
	s_waitcnt lgkmcnt(1)
	v_mfma_f32_16x16x32_bf16 v[134:137], v[206:209], v[236:239], v[134:137]
	v_mfma_f32_16x16x32_bf16 v[138:141], v[206:209], v[240:243], v[138:141]
	v_mfma_f32_16x16x32_bf16 v[142:145], v[206:209], v[244:247], v[142:145]
	v_mfma_f32_16x16x32_bf16 v[126:129], v[206:209], v[248:251], v[126:129]
	s_waitcnt lgkmcnt(0)
	v_mfma_f32_16x16x32_bf16 v[146:149], v[210:213], v[236:239], v[146:149]
	v_mfma_f32_16x16x32_bf16 v[150:153], v[210:213], v[240:243], v[150:153]
	v_mfma_f32_16x16x32_bf16 v[154:157], v[210:213], v[244:247], v[154:157]
	v_mfma_f32_16x16x32_bf16 v[130:133], v[210:213], v[248:251], v[130:133]
	ds_read_b128 v[206:209], v60 offset:49152
	ds_read_b128 v[210:213], v60 offset:57344
	s_waitcnt lgkmcnt(1)
	v_mfma_f32_16x16x32_bf16 v[166:169], v[206:209], v[236:239], v[166:169]
	v_mfma_f32_16x16x32_bf16 v[170:173], v[206:209], v[240:243], v[170:173]
	v_mfma_f32_16x16x32_bf16 v[174:177], v[206:209], v[244:247], v[174:177]
	v_mfma_f32_16x16x32_bf16 v[158:161], v[206:209], v[248:251], v[158:161]
	s_waitcnt lgkmcnt(0)
	v_mfma_f32_16x16x32_bf16 v[4:7], v[210:213], v[236:239], v[4:7]
	v_mfma_f32_16x16x32_bf16 v[8:11], v[210:213], v[240:243], v[8:11]
	v_mfma_f32_16x16x32_bf16 v[24:27], v[210:213], v[244:247], v[24:27]
	v_mfma_f32_16x16x32_bf16 v[32:35], v[210:213], v[248:251], v[32:35]
	v_add_co_u32_e32 v60, vcc, s72, v2
	s_nop 1
	v_addc_co_u32_e32 v61, vcc, 0, v3, vcc
	global_load_dwordx4 v[236:239], v[60:61], off
	global_load_dwordx4 v[240:243], v[60:61], off offset:1024
	global_load_dwordx4 v[244:247], v[60:61], off offset:2048
	global_load_dwordx4 v[248:251], v[60:61], off offset:3072
	v_bitop3_b32 v60, v214, v235, 12 bitop3:0x36
	v_lshlrev_b32_e32 v60, 4, v60
	v_add3_u32 v60, 0, v60, v64
	ds_read_b128 v[206:209], v60
	ds_read_b128 v[210:213], v60 offset:8192
	s_waitcnt vmcnt(11) lgkmcnt(1)
	v_mfma_f32_16x16x32_bf16 v[20:23], v[206:209], v[162:165], v[20:23]
	s_waitcnt vmcnt(10)
	v_mfma_f32_16x16x32_bf16 v[28:31], v[206:209], v[194:197], v[28:31]
	s_waitcnt vmcnt(9)
	v_mfma_f32_16x16x32_bf16 v[36:39], v[206:209], v[198:201], v[36:39]
	s_waitcnt vmcnt(8)
	v_mfma_f32_16x16x32_bf16 v[12:15], v[206:209], v[202:205], v[12:15]
	s_waitcnt lgkmcnt(0)
	v_mfma_f32_16x16x32_bf16 v[40:43], v[210:213], v[162:165], v[40:43]
	v_mfma_f32_16x16x32_bf16 v[44:47], v[210:213], v[194:197], v[44:47]
	v_mfma_f32_16x16x32_bf16 v[48:51], v[210:213], v[198:201], v[48:51]
	v_mfma_f32_16x16x32_bf16 v[16:19], v[210:213], v[202:205], v[16:19]
	ds_read_b128 v[206:209], v60 offset:16384
	ds_read_b128 v[210:213], v60 offset:24576
	s_waitcnt lgkmcnt(1)
	v_mfma_f32_16x16x32_bf16 v[72:75], v[206:209], v[162:165], v[72:75]
	v_mfma_f32_16x16x32_bf16 v[76:79], v[206:209], v[194:197], v[76:79]
	v_mfma_f32_16x16x32_bf16 v[80:83], v[206:209], v[198:201], v[80:83]
	v_mfma_f32_16x16x32_bf16 v[52:55], v[206:209], v[202:205], v[52:55]
	s_waitcnt lgkmcnt(0)
	v_mfma_f32_16x16x32_bf16 v[114:117], v[210:213], v[162:165], v[114:117]
	v_mfma_f32_16x16x32_bf16 v[118:121], v[210:213], v[194:197], v[118:121]
	v_mfma_f32_16x16x32_bf16 v[122:125], v[210:213], v[198:201], v[122:125]
	v_mfma_f32_16x16x32_bf16 v[56:59], v[210:213], v[202:205], v[56:59]
	ds_read_b128 v[206:209], v60 offset:32768
	ds_read_b128 v[210:213], v60 offset:40960
	s_waitcnt lgkmcnt(1)
	v_mfma_f32_16x16x32_bf16 v[134:137], v[206:209], v[162:165], v[134:137]
	v_mfma_f32_16x16x32_bf16 v[138:141], v[206:209], v[194:197], v[138:141]
	v_mfma_f32_16x16x32_bf16 v[142:145], v[206:209], v[198:201], v[142:145]
	v_mfma_f32_16x16x32_bf16 v[126:129], v[206:209], v[202:205], v[126:129]
	s_waitcnt lgkmcnt(0)
	v_mfma_f32_16x16x32_bf16 v[146:149], v[210:213], v[162:165], v[146:149]
	v_mfma_f32_16x16x32_bf16 v[150:153], v[210:213], v[194:197], v[150:153]
	v_mfma_f32_16x16x32_bf16 v[154:157], v[210:213], v[198:201], v[154:157]
	v_mfma_f32_16x16x32_bf16 v[130:133], v[210:213], v[202:205], v[130:133]
	ds_read_b128 v[206:209], v60 offset:49152
	ds_read_b128 v[210:213], v60 offset:57344
	s_waitcnt lgkmcnt(1)
	v_mfma_f32_16x16x32_bf16 v[166:169], v[206:209], v[162:165], v[166:169]
	v_mfma_f32_16x16x32_bf16 v[170:173], v[206:209], v[194:197], v[170:173]
	v_mfma_f32_16x16x32_bf16 v[174:177], v[206:209], v[198:201], v[174:177]
	v_mfma_f32_16x16x32_bf16 v[158:161], v[206:209], v[202:205], v[158:161]
	s_waitcnt lgkmcnt(0)
	v_mfma_f32_16x16x32_bf16 v[4:7], v[210:213], v[162:165], v[4:7]
	v_mfma_f32_16x16x32_bf16 v[8:11], v[210:213], v[194:197], v[8:11]
	v_mfma_f32_16x16x32_bf16 v[24:27], v[210:213], v[198:201], v[24:27]
	v_mfma_f32_16x16x32_bf16 v[32:35], v[210:213], v[202:205], v[32:35]
	v_add_co_u32_e32 v60, vcc, s68, v2
	s_nop 1
	v_addc_co_u32_e32 v61, vcc, 0, v3, vcc
	global_load_dwordx4 v[162:165], v[60:61], off
	global_load_dwordx4 v[194:197], v[60:61], off offset:1024
	global_load_dwordx4 v[198:201], v[60:61], off offset:2048
	global_load_dwordx4 v[202:205], v[60:61], off offset:3072
	v_bitop3_b32 v60, v214, v235, 16 bitop3:0x36
	v_lshlrev_b32_e32 v60, 4, v60
	v_add3_u32 v60, 0, v60, v64
	ds_read_b128 v[206:209], v60
	ds_read_b128 v[210:213], v60 offset:8192
	s_waitcnt vmcnt(11) lgkmcnt(1)
	v_mfma_f32_16x16x32_bf16 v[20:23], v[206:209], v[178:181], v[20:23]
	s_waitcnt vmcnt(10)
	v_mfma_f32_16x16x32_bf16 v[28:31], v[206:209], v[182:185], v[28:31]
	s_waitcnt vmcnt(9)
	v_mfma_f32_16x16x32_bf16 v[36:39], v[206:209], v[186:189], v[36:39]
	s_waitcnt vmcnt(8)
	v_mfma_f32_16x16x32_bf16 v[12:15], v[206:209], v[190:193], v[12:15]
	s_waitcnt lgkmcnt(0)
	v_mfma_f32_16x16x32_bf16 v[40:43], v[210:213], v[178:181], v[40:43]
	v_mfma_f32_16x16x32_bf16 v[44:47], v[210:213], v[182:185], v[44:47]
	v_mfma_f32_16x16x32_bf16 v[48:51], v[210:213], v[186:189], v[48:51]
	v_mfma_f32_16x16x32_bf16 v[16:19], v[210:213], v[190:193], v[16:19]
	ds_read_b128 v[206:209], v60 offset:16384
	ds_read_b128 v[210:213], v60 offset:24576
	s_waitcnt lgkmcnt(1)
	v_mfma_f32_16x16x32_bf16 v[72:75], v[206:209], v[178:181], v[72:75]
	v_mfma_f32_16x16x32_bf16 v[76:79], v[206:209], v[182:185], v[76:79]
	v_mfma_f32_16x16x32_bf16 v[80:83], v[206:209], v[186:189], v[80:83]
	v_mfma_f32_16x16x32_bf16 v[52:55], v[206:209], v[190:193], v[52:55]
	s_waitcnt lgkmcnt(0)
	v_mfma_f32_16x16x32_bf16 v[114:117], v[210:213], v[178:181], v[114:117]
	v_mfma_f32_16x16x32_bf16 v[118:121], v[210:213], v[182:185], v[118:121]
	v_mfma_f32_16x16x32_bf16 v[122:125], v[210:213], v[186:189], v[122:125]
	v_mfma_f32_16x16x32_bf16 v[56:59], v[210:213], v[190:193], v[56:59]
	ds_read_b128 v[206:209], v60 offset:32768
	ds_read_b128 v[210:213], v60 offset:40960
	s_waitcnt lgkmcnt(1)
	v_mfma_f32_16x16x32_bf16 v[134:137], v[206:209], v[178:181], v[134:137]
	v_mfma_f32_16x16x32_bf16 v[138:141], v[206:209], v[182:185], v[138:141]
	v_mfma_f32_16x16x32_bf16 v[142:145], v[206:209], v[186:189], v[142:145]
	v_mfma_f32_16x16x32_bf16 v[126:129], v[206:209], v[190:193], v[126:129]
	s_waitcnt lgkmcnt(0)
	v_mfma_f32_16x16x32_bf16 v[146:149], v[210:213], v[178:181], v[146:149]
	v_mfma_f32_16x16x32_bf16 v[150:153], v[210:213], v[182:185], v[150:153]
	v_mfma_f32_16x16x32_bf16 v[154:157], v[210:213], v[186:189], v[154:157]
	v_mfma_f32_16x16x32_bf16 v[130:133], v[210:213], v[190:193], v[130:133]
	ds_read_b128 v[206:209], v60 offset:49152
	ds_read_b128 v[210:213], v60 offset:57344
	s_waitcnt lgkmcnt(1)
	v_mfma_f32_16x16x32_bf16 v[166:169], v[206:209], v[178:181], v[166:169]
	v_mfma_f32_16x16x32_bf16 v[170:173], v[206:209], v[182:185], v[170:173]
	v_mfma_f32_16x16x32_bf16 v[174:177], v[206:209], v[186:189], v[174:177]
	v_mfma_f32_16x16x32_bf16 v[158:161], v[206:209], v[190:193], v[158:161]
	s_waitcnt lgkmcnt(0)
	v_mfma_f32_16x16x32_bf16 v[4:7], v[210:213], v[178:181], v[4:7]
	v_mfma_f32_16x16x32_bf16 v[8:11], v[210:213], v[182:185], v[8:11]
	v_mfma_f32_16x16x32_bf16 v[24:27], v[210:213], v[186:189], v[24:27]
	v_mfma_f32_16x16x32_bf16 v[32:35], v[210:213], v[190:193], v[32:35]
	v_add_co_u32_e32 v60, vcc, s73, v2
	s_nop 1
	v_addc_co_u32_e32 v61, vcc, 0, v3, vcc
	global_load_dwordx4 v[178:181], v[60:61], off
	global_load_dwordx4 v[182:185], v[60:61], off offset:1024
	global_load_dwordx4 v[186:189], v[60:61], off offset:2048
	global_load_dwordx4 v[190:193], v[60:61], off offset:3072
	v_bitop3_b32 v60, v214, v235, 20 bitop3:0x36
	v_lshlrev_b32_e32 v60, 4, v60
	v_add3_u32 v60, 0, v60, v64
	ds_read_b128 v[206:209], v60
	ds_read_b128 v[210:213], v60 offset:8192
	s_waitcnt vmcnt(11) lgkmcnt(1)
	v_mfma_f32_16x16x32_bf16 v[20:23], v[206:209], v[236:239], v[20:23]
	s_waitcnt vmcnt(10)
	v_mfma_f32_16x16x32_bf16 v[28:31], v[206:209], v[240:243], v[28:31]
	s_waitcnt vmcnt(9)
	v_mfma_f32_16x16x32_bf16 v[36:39], v[206:209], v[244:247], v[36:39]
	s_waitcnt vmcnt(8)
	v_mfma_f32_16x16x32_bf16 v[12:15], v[206:209], v[248:251], v[12:15]
	s_waitcnt lgkmcnt(0)
	v_mfma_f32_16x16x32_bf16 v[40:43], v[210:213], v[236:239], v[40:43]
	v_mfma_f32_16x16x32_bf16 v[44:47], v[210:213], v[240:243], v[44:47]
	v_mfma_f32_16x16x32_bf16 v[48:51], v[210:213], v[244:247], v[48:51]
	v_mfma_f32_16x16x32_bf16 v[16:19], v[210:213], v[248:251], v[16:19]
	ds_read_b128 v[206:209], v60 offset:16384
	ds_read_b128 v[210:213], v60 offset:24576
	s_waitcnt lgkmcnt(1)
	v_mfma_f32_16x16x32_bf16 v[72:75], v[206:209], v[236:239], v[72:75]
	v_mfma_f32_16x16x32_bf16 v[76:79], v[206:209], v[240:243], v[76:79]
	v_mfma_f32_16x16x32_bf16 v[80:83], v[206:209], v[244:247], v[80:83]
	v_mfma_f32_16x16x32_bf16 v[52:55], v[206:209], v[248:251], v[52:55]
	s_waitcnt lgkmcnt(0)
	v_mfma_f32_16x16x32_bf16 v[114:117], v[210:213], v[236:239], v[114:117]
	v_mfma_f32_16x16x32_bf16 v[118:121], v[210:213], v[240:243], v[118:121]
	v_mfma_f32_16x16x32_bf16 v[122:125], v[210:213], v[244:247], v[122:125]
	v_mfma_f32_16x16x32_bf16 v[56:59], v[210:213], v[248:251], v[56:59]
	ds_read_b128 v[206:209], v60 offset:32768
	ds_read_b128 v[210:213], v60 offset:40960
	s_waitcnt lgkmcnt(1)
	v_mfma_f32_16x16x32_bf16 v[134:137], v[206:209], v[236:239], v[134:137]
	v_mfma_f32_16x16x32_bf16 v[138:141], v[206:209], v[240:243], v[138:141]
	v_mfma_f32_16x16x32_bf16 v[142:145], v[206:209], v[244:247], v[142:145]
	v_mfma_f32_16x16x32_bf16 v[126:129], v[206:209], v[248:251], v[126:129]
	s_waitcnt lgkmcnt(0)
	v_mfma_f32_16x16x32_bf16 v[146:149], v[210:213], v[236:239], v[146:149]
	v_mfma_f32_16x16x32_bf16 v[150:153], v[210:213], v[240:243], v[150:153]
	v_mfma_f32_16x16x32_bf16 v[154:157], v[210:213], v[244:247], v[154:157]
	v_mfma_f32_16x16x32_bf16 v[130:133], v[210:213], v[248:251], v[130:133]
	ds_read_b128 v[206:209], v60 offset:49152
	ds_read_b128 v[210:213], v60 offset:57344
	s_waitcnt lgkmcnt(1)
	v_mfma_f32_16x16x32_bf16 v[166:169], v[206:209], v[236:239], v[166:169]
	v_mfma_f32_16x16x32_bf16 v[170:173], v[206:209], v[240:243], v[170:173]
	v_mfma_f32_16x16x32_bf16 v[174:177], v[206:209], v[244:247], v[174:177]
	v_mfma_f32_16x16x32_bf16 v[158:161], v[206:209], v[248:251], v[158:161]
	s_waitcnt lgkmcnt(0)
	v_mfma_f32_16x16x32_bf16 v[4:7], v[210:213], v[236:239], v[4:7]
	v_mfma_f32_16x16x32_bf16 v[8:11], v[210:213], v[240:243], v[8:11]
	v_mfma_f32_16x16x32_bf16 v[24:27], v[210:213], v[244:247], v[24:27]
	v_mfma_f32_16x16x32_bf16 v[32:35], v[210:213], v[248:251], v[32:35]
	v_bitop3_b32 v2, v214, v235, 24 bitop3:0x36
	v_lshlrev_b32_e32 v2, 4, v2
	v_add3_u32 v2, 0, v2, v64
	ds_read_b128 v[206:209], v2
	ds_read_b128 v[210:213], v2 offset:8192
	s_waitcnt vmcnt(7) lgkmcnt(1)
	v_mfma_f32_16x16x32_bf16 v[20:23], v[206:209], v[162:165], v[20:23]
	s_waitcnt vmcnt(6)
	v_mfma_f32_16x16x32_bf16 v[28:31], v[206:209], v[194:197], v[28:31]
	s_waitcnt vmcnt(5)
	v_mfma_f32_16x16x32_bf16 v[36:39], v[206:209], v[198:201], v[36:39]
	s_waitcnt vmcnt(4)
	v_mfma_f32_16x16x32_bf16 v[12:15], v[206:209], v[202:205], v[12:15]
	s_waitcnt lgkmcnt(0)
	v_mfma_f32_16x16x32_bf16 v[40:43], v[210:213], v[162:165], v[40:43]
	v_mfma_f32_16x16x32_bf16 v[44:47], v[210:213], v[194:197], v[44:47]
	v_mfma_f32_16x16x32_bf16 v[48:51], v[210:213], v[198:201], v[48:51]
	v_mfma_f32_16x16x32_bf16 v[16:19], v[210:213], v[202:205], v[16:19]
	ds_read_b128 v[206:209], v2 offset:16384
	ds_read_b128 v[210:213], v2 offset:24576
	s_waitcnt lgkmcnt(1)
	v_mfma_f32_16x16x32_bf16 v[72:75], v[206:209], v[162:165], v[72:75]
	v_mfma_f32_16x16x32_bf16 v[76:79], v[206:209], v[194:197], v[76:79]
	v_mfma_f32_16x16x32_bf16 v[80:83], v[206:209], v[198:201], v[80:83]
	v_mfma_f32_16x16x32_bf16 v[206:209], v[206:209], v[202:205], v[52:55]
	s_waitcnt lgkmcnt(0)
	v_mfma_f32_16x16x32_bf16 v[114:117], v[210:213], v[162:165], v[114:117]
	v_mfma_f32_16x16x32_bf16 v[118:121], v[210:213], v[194:197], v[118:121]
	v_mfma_f32_16x16x32_bf16 v[122:125], v[210:213], v[198:201], v[122:125]
	v_mfma_f32_16x16x32_bf16 v[210:213], v[210:213], v[202:205], v[56:59]
	ds_read_b128 v[52:55], v2 offset:32768
	s_nop 1
	ds_read_b128 v[56:59], v2 offset:40960
	s_waitcnt lgkmcnt(1)
	v_mfma_f32_16x16x32_bf16 v[134:137], v[52:55], v[162:165], v[134:137]
	v_mfma_f32_16x16x32_bf16 v[138:141], v[52:55], v[194:197], v[138:141]
	v_mfma_f32_16x16x32_bf16 v[142:145], v[52:55], v[198:201], v[142:145]
	v_mfma_f32_16x16x32_bf16 v[126:129], v[52:55], v[202:205], v[126:129]
	s_waitcnt lgkmcnt(0)
	v_mfma_f32_16x16x32_bf16 v[146:149], v[56:59], v[162:165], v[146:149]
	v_mfma_f32_16x16x32_bf16 v[150:153], v[56:59], v[194:197], v[150:153]
	v_mfma_f32_16x16x32_bf16 v[154:157], v[56:59], v[198:201], v[154:157]
	v_mfma_f32_16x16x32_bf16 v[130:133], v[56:59], v[202:205], v[130:133]
	ds_read_b128 v[52:55], v2 offset:49152
	ds_read_b128 v[56:59], v2 offset:57344
	s_waitcnt lgkmcnt(1)
	v_mfma_f32_16x16x32_bf16 v[166:169], v[52:55], v[162:165], v[166:169]
	v_mfma_f32_16x16x32_bf16 v[170:173], v[52:55], v[194:197], v[170:173]
	v_mfma_f32_16x16x32_bf16 v[174:177], v[52:55], v[198:201], v[174:177]
	v_mfma_f32_16x16x32_bf16 v[158:161], v[52:55], v[202:205], v[158:161]
	s_waitcnt lgkmcnt(0)
	v_mfma_f32_16x16x32_bf16 v[162:165], v[56:59], v[162:165], v[4:7]
	v_mfma_f32_16x16x32_bf16 v[6:9], v[56:59], v[194:197], v[8:11]
	v_mfma_f32_16x16x32_bf16 v[194:197], v[56:59], v[198:201], v[24:27]
	v_mfma_f32_16x16x32_bf16 v[198:201], v[56:59], v[202:205], v[32:35]
	v_bitop3_b32 v2, v214, v235, 28 bitop3:0x36
	v_lshlrev_b32_e32 v2, 4, v2
	v_add3_u32 v64, 0, v2, v64
	ds_read_b128 v[2:5], v64
	ds_read_b128 v[32:35], v64 offset:8192
	s_waitcnt vmcnt(3) lgkmcnt(1)
	v_mfma_f32_16x16x32_bf16 v[202:205], v[2:5], v[178:181], v[20:23]
	s_waitcnt vmcnt(2)
	v_mfma_f32_16x16x32_bf16 v[214:217], v[2:5], v[182:185], v[28:31]
	s_waitcnt vmcnt(1)
	v_mfma_f32_16x16x32_bf16 v[58:61], v[2:5], v[186:189], v[36:39]
	s_waitcnt vmcnt(0)
	v_mfma_f32_16x16x32_bf16 v[26:29], v[2:5], v[190:193], v[12:15]
	ds_read_b128 v[2:5], v64 offset:16384
	s_nop 1
	ds_read_b128 v[10:13], v64 offset:24576
	s_waitcnt lgkmcnt(2)
	v_mfma_f32_16x16x32_bf16 v[218:221], v[32:35], v[178:181], v[40:43]
	v_mfma_f32_16x16x32_bf16 v[222:225], v[32:35], v[182:185], v[44:47]
	v_mfma_f32_16x16x32_bf16 v[226:229], v[32:35], v[186:189], v[48:51]
	v_mfma_f32_16x16x32_bf16 v[30:33], v[32:35], v[190:193], v[16:19]
	s_waitcnt lgkmcnt(1)
	v_mfma_f32_16x16x32_bf16 v[230:233], v[2:5], v[178:181], v[72:75]
	v_mfma_f32_16x16x32_bf16 v[74:77], v[2:5], v[182:185], v[76:79]
	v_mfma_f32_16x16x32_bf16 v[50:53], v[2:5], v[186:189], v[80:83]
	v_mfma_f32_16x16x32_bf16 v[18:21], v[2:5], v[190:193], v[206:209]
	ds_read_b128 v[2:5], v64 offset:32768
	ds_read_b128 v[14:17], v64 offset:40960
	s_waitcnt lgkmcnt(2)
	v_mfma_f32_16x16x32_bf16 v[78:81], v[10:13], v[178:181], v[114:117]
	v_mfma_f32_16x16x32_bf16 v[114:117], v[10:13], v[182:185], v[118:121]
	v_mfma_f32_16x16x32_bf16 v[54:57], v[10:13], v[186:189], v[122:125]
	v_mfma_f32_16x16x32_bf16 v[22:25], v[10:13], v[190:193], v[210:213]
	s_waitcnt lgkmcnt(1)
	v_mfma_f32_16x16x32_bf16 v[118:121], v[2:5], v[178:181], v[134:137]
	v_mfma_f32_16x16x32_bf16 v[122:125], v[2:5], v[182:185], v[138:141]
	v_mfma_f32_16x16x32_bf16 v[42:45], v[2:5], v[186:189], v[142:145]
	v_mfma_f32_16x16x32_bf16 v[10:13], v[2:5], v[190:193], v[126:129]
	s_waitcnt lgkmcnt(0)
	v_mfma_f32_16x16x32_bf16 v[126:129], v[14:17], v[178:181], v[146:149]
	v_mfma_f32_16x16x32_bf16 v[134:137], v[14:17], v[182:185], v[150:153]
	v_mfma_f32_16x16x32_bf16 v[46:49], v[14:17], v[186:189], v[154:157]
	v_mfma_f32_16x16x32_bf16 v[14:17], v[14:17], v[190:193], v[130:133]
	ds_read_b128 v[2:5], v64 offset:49152
	s_nop 1
	ds_read_b128 v[130:133], v64 offset:57344
	s_waitcnt lgkmcnt(1)
	v_mfma_f32_16x16x32_bf16 v[138:141], v[2:5], v[178:181], v[166:169]
	v_mfma_f32_16x16x32_bf16 v[142:145], v[2:5], v[182:185], v[170:173]
	v_mfma_f32_16x16x32_bf16 v[34:37], v[2:5], v[186:189], v[174:177]
	v_mfma_f32_16x16x32_bf16 v[2:5], v[2:5], v[190:193], v[158:161]
	s_waitcnt lgkmcnt(0)
	v_mfma_f32_16x16x32_bf16 v[146:149], v[130:133], v[178:181], v[162:165]
	v_mfma_f32_16x16x32_bf16 v[150:153], v[130:133], v[182:185], v[6:9]
	v_mfma_f32_16x16x32_bf16 v[38:41], v[130:133], v[186:189], v[194:197]
	v_mfma_f32_16x16x32_bf16 v[6:9], v[130:133], v[190:193], v[198:201]
	s_ashr_i32 s45, s44, 31
	s_lshl_b64 s[46:47], s[44:45], 9
	s_add_u32 s0, s46, s59
	s_addc_u32 s45, s47, s60
	v_or_b32_e32 v72, s0, v235
	v_mov_b32_e32 v73, s45
	v_lshlrev_b64 v[72:73], 8, v[72:73]
	v_and_b32_e32 v64, 16, v234
	v_lshl_add_u64 v[72:73], s[20:21], 0, v[72:73]
	v_lshlrev_b32_e32 v64, 1, v64
	v_lshl_add_u64 v[72:73], v[72:73], 0, v[64:65]
	v_lshrrev_b32_e32 v64, 1, v234
	v_and_b32_e32 v64, 16, v64
	v_lshl_add_u64 v[72:73], v[72:73], 0, v[64:65]
	v_permlane16_swap_b32_e32 v202, v218
	v_permlane16_swap_b32_e32 v203, v219
	v_permlane16_swap_b32_e32 v204, v220
	v_permlane16_swap_b32_e32 v205, v221
	v_add_co_u32_e32 v82, vcc, s62, v72
	v_cvt_pk_bf16_f32 v130, v202, v203
	v_cvt_pk_bf16_f32 v131, v204, v205
	v_cvt_pk_bf16_f32 v132, v218, v219
	v_cvt_pk_bf16_f32 v133, v220, v221
	v_permlane16_swap_b32_e32 v230, v78
	v_permlane16_swap_b32_e32 v231, v79
	v_permlane16_swap_b32_e32 v118, v126
	v_permlane16_swap_b32_e32 v119, v127
	v_addc_co_u32_e32 v83, vcc, 0, v73, vcc
	global_store_dwordx4 v[72:73], v[130:133], off
	v_permlane16_swap_b32_e32 v232, v80
	v_permlane16_swap_b32_e32 v233, v81
	v_cvt_pk_bf16_f32 v132, v78, v79
	v_permlane16_swap_b32_e32 v120, v128
	v_permlane16_swap_b32_e32 v121, v129
	v_cvt_pk_bf16_f32 v78, v118, v119
	v_add_co_u32_e32 v118, vcc, s61, v72
	v_permlane16_swap_b32_e32 v74, v114
	v_permlane16_swap_b32_e32 v75, v115
	v_permlane16_swap_b32_e32 v76, v116
	v_permlane16_swap_b32_e32 v77, v117
	v_cvt_pk_bf16_f32 v133, v80, v81
	v_cvt_pk_bf16_f32 v79, v120, v121
	v_cvt_pk_bf16_f32 v80, v126, v127
	v_cvt_pk_bf16_f32 v81, v128, v129
	v_permlane16_swap_b32_e32 v138, v146
	v_permlane16_swap_b32_e32 v139, v147
	v_permlane16_swap_b32_e32 v140, v148
	v_permlane16_swap_b32_e32 v141, v149
	v_addc_co_u32_e32 v119, vcc, 0, v73, vcc
	v_cvt_pk_bf16_f32 v74, v74, v75
	v_cvt_pk_bf16_f32 v75, v76, v77
	v_cvt_pk_bf16_f32 v76, v114, v115
	v_cvt_pk_bf16_f32 v77, v116, v117
	v_permlane16_swap_b32_e32 v122, v134
	v_permlane16_swap_b32_e32 v123, v135
	v_permlane16_swap_b32_e32 v124, v136
	v_permlane16_swap_b32_e32 v125, v137
	v_permlane16_swap_b32_e32 v26, v30
	v_permlane16_swap_b32_e32 v27, v31
	v_permlane16_swap_b32_e32 v28, v32
	v_permlane16_swap_b32_e32 v29, v33
	global_store_dwordx4 v[72:73], v[78:81], off offset:128
	v_permlane16_swap_b32_e32 v214, v222
	s_nop 0
	v_cvt_pk_bf16_f32 v78, v138, v139
	v_cvt_pk_bf16_f32 v79, v140, v141
	v_cvt_pk_bf16_f32 v80, v146, v147
	v_cvt_pk_bf16_f32 v81, v148, v149
	v_permlane16_swap_b32_e32 v215, v223
	v_permlane16_swap_b32_e32 v216, v224
	v_permlane16_swap_b32_e32 v217, v225
	global_store_dwordx4 v[82:83], v[74:77], off offset:64
	v_permlane16_swap_b32_e32 v142, v150
	s_nop 0
	v_cvt_pk_bf16_f32 v74, v122, v123
	v_cvt_pk_bf16_f32 v75, v124, v125
	v_cvt_pk_bf16_f32 v76, v134, v135
	v_cvt_pk_bf16_f32 v77, v136, v137
	v_permlane16_swap_b32_e32 v143, v151
	v_permlane16_swap_b32_e32 v144, v152
	v_permlane16_swap_b32_e32 v145, v153
	v_permlane16_swap_b32_e32 v58, v226
	v_permlane16_swap_b32_e32 v59, v227
	v_permlane16_swap_b32_e32 v60, v228
	v_permlane16_swap_b32_e32 v61, v229
	v_permlane16_swap_b32_e32 v50, v54
	v_permlane16_swap_b32_e32 v51, v55
	v_permlane16_swap_b32_e32 v52, v56
	v_permlane16_swap_b32_e32 v53, v57
	v_permlane16_swap_b32_e32 v42, v46
	v_permlane16_swap_b32_e32 v43, v47
	v_permlane16_swap_b32_e32 v44, v48
	v_permlane16_swap_b32_e32 v45, v49
	v_permlane16_swap_b32_e32 v34, v38
	v_permlane16_swap_b32_e32 v35, v39
	v_permlane16_swap_b32_e32 v36, v40
	v_permlane16_swap_b32_e32 v37, v41
	v_cvt_pk_bf16_f32 v26, v26, v27
	v_cvt_pk_bf16_f32 v27, v28, v29
	v_cvt_pk_bf16_f32 v28, v30, v31
	v_add_co_u32_e32 v30, vcc, s63, v72
	v_permlane16_swap_b32_e32 v18, v22
	v_permlane16_swap_b32_e32 v19, v23
	v_permlane16_swap_b32_e32 v20, v24
	v_permlane16_swap_b32_e32 v21, v25
	v_permlane16_swap_b32_e32 v10, v14
	v_permlane16_swap_b32_e32 v11, v15
	v_permlane16_swap_b32_e32 v12, v16
	v_permlane16_swap_b32_e32 v13, v17
	v_permlane16_swap_b32_e32 v2, v6
	v_permlane16_swap_b32_e32 v3, v7
	v_permlane16_swap_b32_e32 v4, v8
	v_permlane16_swap_b32_e32 v5, v9
	s_add_i32 s44, s44, s52
	v_cvt_pk_bf16_f32 v130, v230, v231
	v_cvt_pk_bf16_f32 v131, v232, v233
	global_store_dwordx4 v[72:73], v[78:81], off offset:192
	global_store_dwordx4 v[82:83], v[74:77], off offset:128
	v_cvt_pk_bf16_f32 v58, v58, v59
	v_cvt_pk_bf16_f32 v78, v214, v215
	v_cvt_pk_bf16_f32 v79, v216, v217
	v_cvt_pk_bf16_f32 v80, v222, v223
	v_cvt_pk_bf16_f32 v81, v224, v225
	v_cvt_pk_bf16_f32 v74, v142, v143
	v_cvt_pk_bf16_f32 v75, v144, v145
	v_cvt_pk_bf16_f32 v76, v150, v151
	v_cvt_pk_bf16_f32 v77, v152, v153
	v_cvt_pk_bf16_f32 v59, v60, v61
	v_cvt_pk_bf16_f32 v60, v226, v227
	v_cvt_pk_bf16_f32 v61, v228, v229
	v_cvt_pk_bf16_f32 v50, v50, v51
	v_cvt_pk_bf16_f32 v51, v52, v53
	v_cvt_pk_bf16_f32 v52, v54, v55
	v_cvt_pk_bf16_f32 v53, v56, v57
	v_cvt_pk_bf16_f32 v42, v42, v43
	v_cvt_pk_bf16_f32 v43, v44, v45
	v_cvt_pk_bf16_f32 v44, v46, v47
	v_cvt_pk_bf16_f32 v45, v48, v49
	v_cvt_pk_bf16_f32 v34, v34, v35
	v_cvt_pk_bf16_f32 v35, v36, v37
	v_cvt_pk_bf16_f32 v36, v38, v39
	v_cvt_pk_bf16_f32 v37, v40, v41
	v_cvt_pk_bf16_f32 v29, v32, v33
	v_addc_co_u32_e32 v31, vcc, 0, v73, vcc
	v_cvt_pk_bf16_f32 v18, v18, v19
	v_cvt_pk_bf16_f32 v19, v20, v21
	v_cvt_pk_bf16_f32 v20, v22, v23
	v_cvt_pk_bf16_f32 v21, v24, v25
	v_cvt_pk_bf16_f32 v10, v10, v11
	v_cvt_pk_bf16_f32 v11, v12, v13
	v_cvt_pk_bf16_f32 v12, v14, v15
	v_cvt_pk_bf16_f32 v13, v16, v17
	v_cvt_pk_bf16_f32 v2, v2, v3
	v_cvt_pk_bf16_f32 v3, v4, v5
	v_cvt_pk_bf16_f32 v4, v6, v7
	v_cvt_pk_bf16_f32 v5, v8, v9
	s_cmpk_lt_i32 s44, 0x100
	global_store_dwordx4 v[72:73], v[130:133], off offset:64
	global_store_dwordx4 v[118:119], v[78:81], off offset:-4096
	global_store_dwordx4 v[82:83], v[74:77], off offset:192
	global_store_dwordx4 v[118:119], v[58:61], off
	global_store_dwordx4 v[118:119], v[50:53], off offset:64
	global_store_dwordx4 v[118:119], v[42:45], off offset:128
	global_store_dwordx4 v[118:119], v[34:37], off offset:192
	global_store_dwordx4 v[30:31], v[26:29], off
	global_store_dwordx4 v[30:31], v[18:21], off offset:64
	global_store_dwordx4 v[30:31], v[10:13], off offset:128
	global_store_dwordx4 v[30:31], v[2:5], off offset:192
	s_cbranch_scc0 .LBB0_279
